# MLA loop: K/V stage LDS-DMA issue moved to head of step A (one full tile of latency cover), on top of deeper ds_read prefetch
# speedup vs baseline: 1.0067x; 1.0067x over previous
.LBB0_859:
	ds_read_b128 v[236:239], v214 offset:8192
	ds_read_b128 v[240:243], v215 offset:8192
	ds_read_b128 v[244:247], v216 offset:8192
	ds_read_b128 v[248:251], v217 offset:8192
	v_exp_f32_e32 v97, v97
	v_exp_f32_e32 v99, v99
	v_exp_f32_e32 v100, v100
	v_exp_f32_e32 v101, v101
	v_exp_f32_e32 v102, v102
	v_exp_f32_e32 v103, v103
	v_exp_f32_e32 v106, v106
	v_exp_f32_e32 v107, v107
	s_waitcnt lgkmcnt(3)
	v_mfma_f32_32x32x16_bf16 v[80:95], v[236:239], v[144:147], v[64:79]
	ds_read_b128 v[252:255], v218 offset:8192
	v_exp_f32_e32 v108, v108
	v_exp_f32_e32 v109, v109
	v_exp_f32_e32 v110, v110
	v_exp_f32_e32 v111, v111
	s_waitcnt lgkmcnt(3)
	v_mfma_f32_32x32x16_bf16 v[80:95], v[240:243], v[156:159], v[80:95]
	s_add_u32 s98, s34, s60
	s_addc_u32 s99, s35, s59
	s_add_u32 s98, s98, 0x140fc000
	s_addc_u32 s99, s99, 0
	s_add_u32 s100, s34, s62
	s_addc_u32 s101, s35, s61
	s_add_u32 s100, s100, 0x171b0100
	s_addc_u32 s101, s101, 0
	s_cmp_lg_u64 s[24:25], 0
	s_cselect_b32 s4, s100, s98
	s_cselect_b32 s5, s101, s99
	s_mov_b32 m0, s52
	v_mov_b32_e32 v234, s4
	v_mov_b32_e32 v235, s5
	v_lshl_add_u64 v[234:235], v[176:177], 1, v[234:235]
	global_load_lds_dwordx4 v[234:235], off
	s_cmp_lg_u64 s[26:27], 0
	s_cselect_b32 s4, s100, s98
	s_cselect_b32 s5, s101, s99
	s_mov_b32 m0, s53
	v_mov_b32_e32 v234, s4
	v_mov_b32_e32 v235, s5
	v_lshl_add_u64 v[234:235], v[178:179], 1, v[234:235]
	global_load_lds_dwordx4 v[234:235], off
	s_cmp_lg_u64 s[28:29], 0
	s_cselect_b32 s4, s100, s98
	s_cselect_b32 s5, s101, s99
	s_mov_b32 m0, s54
	v_mov_b32_e32 v234, s4
	v_mov_b32_e32 v235, s5
	v_lshl_add_u64 v[234:235], v[180:181], 1, v[234:235]
	global_load_lds_dwordx4 v[234:235], off
	s_cmp_lg_u64 s[30:31], 0
	s_cselect_b32 s4, s100, s98
	s_cselect_b32 s5, s101, s99
	s_mov_b32 m0, s55
	v_mov_b32_e32 v234, s4
	v_mov_b32_e32 v235, s5
	v_lshl_add_u64 v[234:235], v[182:183], 1, v[234:235]
	global_load_lds_dwordx4 v[234:235], off
	s_cmp_lg_u64 s[6:7], 0
	s_cselect_b32 s4, s100, s98
	s_cselect_b32 s5, s101, s99
	s_mov_b32 m0, s56
	v_mov_b32_e32 v234, s4
	v_mov_b32_e32 v235, s5
	v_lshl_add_u64 v[234:235], v[184:185], 1, v[234:235]
	global_load_lds_dwordx4 v[234:235], off
	ds_read_b128 v[236:239], v219 offset:8192
	s_waitcnt lgkmcnt(3)
	v_mfma_f32_32x32x16_bf16 v[80:95], v[244:247], v[168:171], v[80:95]
	ds_read_b128 v[240:243], v220 offset:8192
	s_waitcnt lgkmcnt(3)
	v_mfma_f32_32x32x16_bf16 v[80:95], v[248:251], v[172:175], v[80:95]
	ds_read_b128 v[244:247], v221 offset:8192
	s_waitcnt lgkmcnt(3)
	v_mfma_f32_32x32x16_bf16 v[80:95], v[252:255], v[164:167], v[80:95]
	ds_read_b128 v[248:251], v205 offset:53248
	s_waitcnt lgkmcnt(3)
	v_mfma_f32_32x32x16_bf16 v[80:95], v[236:239], v[160:163], v[80:95]
	ds_read_b128 v[252:255], v207 offset:53248
	s_waitcnt lgkmcnt(3)
	v_mfma_f32_32x32x16_bf16 v[80:95], v[240:243], v[152:155], v[80:95]
	ds_read_b128 v[236:239], v209 offset:53248
	s_waitcnt lgkmcnt(3)
	v_mfma_f32_32x32x16_bf16 v[80:95], v[244:247], v[148:151], v[80:95]
	ds_read_b128 v[240:243], v211 offset:53248
	s_waitcnt lgkmcnt(3)
	v_mfma_f32_32x32x16_bf16 v[80:95], v[248:251], v[140:143], v[80:95]
	ds_read_b128 v[244:247], v225
	s_waitcnt lgkmcnt(3)
	v_mfma_f32_32x32x16_bf16 v[80:95], v[252:255], v[136:139], v[80:95]
	ds_read_b128 v[248:251], v225 offset:4096
	s_waitcnt lgkmcnt(3)
	v_mfma_f32_32x32x16_bf16 v[80:95], v[236:239], v[132:135], v[80:95]
	ds_read_b128 v[252:255], v225 offset:8192
	s_waitcnt lgkmcnt(3)
	v_mfma_f32_32x32x16_bf16 v[80:95], v[240:243], v[128:131], v[80:95]
	ds_read_b128 v[236:239], v225 offset:12288
	v_exp_f32_e32 v112, v96
	v_exp_f32_e32 v113, v98
	v_exp_f32_e32 v114, v104
	v_exp_f32_e32 v115, v105
	v_add_f32_e32 v96, 0, v112
	v_add_f32_e32 v96, v97, v96
	v_add_f32_e32 v96, v113, v96
	v_add_f32_e32 v96, v99, v96
	v_add_f32_e32 v96, v100, v96
	v_add_f32_e32 v96, v101, v96
	v_add_f32_e32 v96, v102, v96
	v_add_f32_e32 v96, v103, v96
	v_cvt_pk_bf16_f32 v100, v100, v101
	v_cvt_pk_bf16_f32 v101, v102, v103
	v_cvt_pk_bf16_f32 v98, v112, v97
	v_cvt_pk_bf16_f32 v99, v113, v99
	v_max_f32_e32 v97, v81, v81
	v_add_f32_e32 v96, v114, v96
	s_waitcnt lgkmcnt(3)
	v_mfma_f32_32x32x16_bf16 v[48:63], v[244:247], v[98:101], v[48:63]
	ds_read_b128 v[240:243], v226
	v_add_f32_e32 v96, v115, v96
	v_add_f32_e32 v96, v106, v96
	v_add_f32_e32 v96, v107, v96
	v_add_f32_e32 v96, v108, v96
	v_add_f32_e32 v96, v109, v96
	v_add_f32_e32 v96, v110, v96
	s_waitcnt lgkmcnt(3)
	v_mfma_f32_32x32x16_bf16 v[32:47], v[248:251], v[98:101], v[32:47]
	ds_read_b128 v[244:247], v226 offset:4096
	v_add_f32_e32 v96, v111, v96
	v_add_f32_e32 v112, v230, v96
	s_waitcnt lgkmcnt(3)
	v_mfma_f32_32x32x16_bf16 v[16:31], v[252:255], v[98:101], v[16:31]
	ds_read_b128 v[248:251], v226 offset:8192
	s_waitcnt lgkmcnt(3)
	v_mfma_f32_32x32x16_bf16 v[0:15], v[236:239], v[98:101], v[0:15]
	ds_read_b128 v[252:255], v226 offset:12288
	v_cvt_pk_bf16_f32 v98, v114, v115
	v_cvt_pk_bf16_f32 v99, v106, v107
	v_cvt_pk_bf16_f32 v100, v108, v109
	v_cvt_pk_bf16_f32 v101, v110, v111
	s_nop 0
	s_waitcnt lgkmcnt(3)
	v_mfma_f32_32x32x16_bf16 v[48:63], v[240:243], v[98:101], v[48:63]
	ds_read_b128 v[236:239], v214 offset:16384
	s_waitcnt lgkmcnt(3)
	v_mfma_f32_32x32x16_bf16 v[32:47], v[244:247], v[98:101], v[32:47]
	ds_read_b128 v[240:243], v215 offset:16384
	s_waitcnt lgkmcnt(3)
	v_mfma_f32_32x32x16_bf16 v[16:31], v[248:251], v[98:101], v[16:31]
	ds_read_b128 v[244:247], v216 offset:16384
	s_waitcnt lgkmcnt(3)
	v_mfma_f32_32x32x16_bf16 v[0:15], v[252:255], v[98:101], v[0:15]
	ds_read_b128 v[248:251], v217 offset:16384
	v_max_f32_e32 v98, v80, v80
	v_max_f32_e32 v97, v98, v97
	v_max3_f32 v97, v97, v82, v83
	v_max3_f32 v97, v97, v84, v85
	v_max3_f32 v97, v97, v86, v87
	v_max3_f32 v97, v97, v88, v89
	v_max3_f32 v97, v97, v90, v91
	v_max3_f32 v97, v97, v92, v93
	v_max3_f32 v97, v97, v94, v95
	ds_bpermute_b32 v98, v229, v97
	s_waitcnt lgkmcnt(0)
	v_max_f32_e32 v96, v98, v98
	v_max_f32_e32 v96, v97, v96
	v_cmp_lt_f32_e32 vcc, 0, v96
	s_cbranch_vccz .LBB0_861
	v_max_f32_e32 v96, v96, v96
	v_max_f32_e32 v96, 0, v96
	v_exp_f32_e64 v98, -v96
	v_pk_add_f32 v[80:81], v[80:81], v[96:97] op_sel_hi:[1,0] neg_lo:[0,1] neg_hi:[0,1]
	v_pk_add_f32 v[82:83], v[82:83], v[96:97] op_sel_hi:[1,0] neg_lo:[0,1] neg_hi:[0,1]
	v_pk_add_f32 v[84:85], v[84:85], v[96:97] op_sel_hi:[1,0] neg_lo:[0,1] neg_hi:[0,1]
	v_mul_f32_e32 v112, v112, v98
	v_pk_add_f32 v[86:87], v[86:87], v[96:97] op_sel_hi:[1,0] neg_lo:[0,1] neg_hi:[0,1]
	v_pk_add_f32 v[88:89], v[88:89], v[96:97] op_sel_hi:[1,0] neg_lo:[0,1] neg_hi:[0,1]
	v_pk_add_f32 v[90:91], v[90:91], v[96:97] op_sel_hi:[1,0] neg_lo:[0,1] neg_hi:[0,1]
	v_pk_add_f32 v[92:93], v[92:93], v[96:97] op_sel_hi:[1,0] neg_lo:[0,1] neg_hi:[0,1]
	v_sub_f32_e32 v79, v79, v96
	v_sub_f32_e32 v78, v78, v96
	v_sub_f32_e32 v77, v77, v96
	v_sub_f32_e32 v76, v76, v96
	v_sub_f32_e32 v75, v75, v96
	v_sub_f32_e32 v74, v74, v96
	v_sub_f32_e32 v73, v73, v96
	v_sub_f32_e32 v72, v72, v96
	v_sub_f32_e32 v71, v71, v96
	v_sub_f32_e32 v70, v70, v96
	v_sub_f32_e32 v69, v69, v96
	v_sub_f32_e32 v68, v68, v96
	v_sub_f32_e32 v67, v67, v96
	v_sub_f32_e32 v66, v66, v96
	v_sub_f32_e32 v65, v65, v96
	v_sub_f32_e32 v64, v64, v96
	v_pk_add_f32 v[94:95], v[94:95], v[96:97] op_sel_hi:[1,0] neg_lo:[0,1] neg_hi:[0,1]
	v_pk_mul_f32 v[62:63], v[62:63], v[98:99] op_sel_hi:[1,0]
	v_pk_mul_f32 v[60:61], v[60:61], v[98:99] op_sel_hi:[1,0]
	v_pk_mul_f32 v[58:59], v[58:59], v[98:99] op_sel_hi:[1,0]
	v_pk_mul_f32 v[56:57], v[56:57], v[98:99] op_sel_hi:[1,0]
	v_pk_mul_f32 v[54:55], v[54:55], v[98:99] op_sel_hi:[1,0]
	v_pk_mul_f32 v[52:53], v[52:53], v[98:99] op_sel_hi:[1,0]
	v_pk_mul_f32 v[50:51], v[50:51], v[98:99] op_sel_hi:[1,0]
	v_pk_mul_f32 v[48:49], v[48:49], v[98:99] op_sel_hi:[1,0]
	v_pk_mul_f32 v[46:47], v[46:47], v[98:99] op_sel_hi:[1,0]
	v_pk_mul_f32 v[44:45], v[44:45], v[98:99] op_sel_hi:[1,0]
	v_pk_mul_f32 v[42:43], v[42:43], v[98:99] op_sel_hi:[1,0]
	v_pk_mul_f32 v[40:41], v[40:41], v[98:99] op_sel_hi:[1,0]
	v_pk_mul_f32 v[38:39], v[38:39], v[98:99] op_sel_hi:[1,0]
	v_pk_mul_f32 v[36:37], v[36:37], v[98:99] op_sel_hi:[1,0]
	v_pk_mul_f32 v[34:35], v[34:35], v[98:99] op_sel_hi:[1,0]
	v_pk_mul_f32 v[32:33], v[32:33], v[98:99] op_sel_hi:[1,0]
	v_pk_mul_f32 v[30:31], v[30:31], v[98:99] op_sel_hi:[1,0]
	v_pk_mul_f32 v[28:29], v[28:29], v[98:99] op_sel_hi:[1,0]
	v_pk_mul_f32 v[26:27], v[26:27], v[98:99] op_sel_hi:[1,0]
	v_pk_mul_f32 v[24:25], v[24:25], v[98:99] op_sel_hi:[1,0]
	v_pk_mul_f32 v[22:23], v[22:23], v[98:99] op_sel_hi:[1,0]
	v_pk_mul_f32 v[20:21], v[20:21], v[98:99] op_sel_hi:[1,0]
	v_pk_mul_f32 v[18:19], v[18:19], v[98:99] op_sel_hi:[1,0]
	v_pk_mul_f32 v[16:17], v[16:17], v[98:99] op_sel_hi:[1,0]
	v_pk_mul_f32 v[14:15], v[14:15], v[98:99] op_sel_hi:[1,0]
	v_pk_mul_f32 v[12:13], v[12:13], v[98:99] op_sel_hi:[1,0]
	v_pk_mul_f32 v[10:11], v[10:11], v[98:99] op_sel_hi:[1,0]
	v_pk_mul_f32 v[8:9], v[8:9], v[98:99] op_sel_hi:[1,0]
	v_pk_mul_f32 v[6:7], v[6:7], v[98:99] op_sel_hi:[1,0]
	v_pk_mul_f32 v[4:5], v[4:5], v[98:99] op_sel_hi:[1,0]
	v_pk_mul_f32 v[2:3], v[2:3], v[98:99] op_sel_hi:[1,0]
	v_pk_mul_f32 v[0:1], v[0:1], v[98:99] op_sel_hi:[1,0]

.LBB0_863:
	v_exp_f32_e32 v96, v96
	v_exp_f32_e32 v97, v97
	v_exp_f32_e32 v98, v98
	v_mfma_f32_32x32x16_bf16 v[80:95], v[236:239], v[144:147], v[64:79]
	ds_read_b128 v[252:255], v218 offset:24576
	v_exp_f32_e32 v99, v99
	v_exp_f32_e32 v100, v100
	v_exp_f32_e32 v101, v101
	v_exp_f32_e32 v102, v102
	v_exp_f32_e32 v103, v103
	v_cvt_pk_bf16_f32 v122, v96, v97
	v_cvt_pk_bf16_f32 v123, v98, v99
	s_waitcnt lgkmcnt(3)
	v_mfma_f32_32x32x16_bf16 v[80:95], v[240:243], v[156:159], v[80:95]
	s_add_i32 s4, s8, 3
	s_cmp_ge_u32 s4, s9
	s_cbranch_scc1 .Lmla_dma_skip_t1
	s_add_u32 s98, s34, s60
	s_addc_u32 s99, s35, s59
	s_add_u32 s98, s98, 0x14102000
	s_addc_u32 s99, s99, 0
	s_add_u32 s100, s34, s62
	s_addc_u32 s101, s35, s61
	s_add_u32 s100, s100, 0x171b0180
	s_addc_u32 s101, s101, 0
	s_cmp_lg_u64 s[24:25], 0
	s_cselect_b32 s4, s100, s98
	s_cselect_b32 s5, s101, s99
	s_mov_b32 m0, s41
	v_mov_b32_e32 v234, s4
	v_mov_b32_e32 v235, s5
	v_lshl_add_u64 v[234:235], v[176:177], 1, v[234:235]
	global_load_lds_dwordx4 v[234:235], off
	s_cmp_lg_u64 s[26:27], 0
	s_cselect_b32 s4, s100, s98
	s_cselect_b32 s5, s101, s99
	s_mov_b32 m0, s42
	v_mov_b32_e32 v234, s4
	v_mov_b32_e32 v235, s5
	v_lshl_add_u64 v[234:235], v[178:179], 1, v[234:235]
	global_load_lds_dwordx4 v[234:235], off
	s_cmp_lg_u64 s[28:29], 0
	s_cselect_b32 s4, s100, s98
	s_cselect_b32 s5, s101, s99
	s_mov_b32 m0, s43
	v_mov_b32_e32 v234, s4
	v_mov_b32_e32 v235, s5
	v_lshl_add_u64 v[234:235], v[180:181], 1, v[234:235]
	global_load_lds_dwordx4 v[234:235], off
	s_cmp_lg_u64 s[30:31], 0
	s_cselect_b32 s4, s100, s98
	s_cselect_b32 s5, s101, s99
	s_mov_b32 m0, s44
	v_mov_b32_e32 v234, s4
	v_mov_b32_e32 v235, s5
	v_lshl_add_u64 v[234:235], v[182:183], 1, v[234:235]
	global_load_lds_dwordx4 v[234:235], off
	s_cmp_lg_u64 s[6:7], 0
	s_cselect_b32 s4, s100, s98
	s_cselect_b32 s5, s101, s99
	s_mov_b32 m0, s45
	v_mov_b32_e32 v234, s4
	v_mov_b32_e32 v235, s5
	v_lshl_add_u64 v[234:235], v[184:185], 1, v[234:235]
	global_load_lds_dwordx4 v[234:235], off
.Lmla_dma_skip_t1:
	ds_read_b128 v[236:239], v219 offset:24576
	v_cvt_pk_bf16_f32 v124, v100, v101
	v_cvt_pk_bf16_f32 v125, v102, v103
	v_exp_f32_e32 v104, v104
	v_exp_f32_e32 v105, v105
	v_exp_f32_e32 v106, v106
	v_exp_f32_e32 v107, v107
	s_waitcnt lgkmcnt(3)
	v_mfma_f32_32x32x16_bf16 v[80:95], v[244:247], v[168:171], v[80:95]
	ds_read_b128 v[240:243], v220 offset:24576
	v_exp_f32_e32 v108, v108
	v_exp_f32_e32 v109, v109
	v_exp_f32_e32 v110, v110
	v_exp_f32_e32 v111, v111
	s_add_i32 s16, s8, 3
	s_cmp_lt_u32 s16, s9
	s_cselect_b64 s[10:11], -1, 0
	s_waitcnt lgkmcnt(3)
	v_mfma_f32_32x32x16_bf16 v[80:95], v[248:251], v[172:175], v[80:95]
	ds_read_b128 v[244:247], v221 offset:24576
	s_cmp_ge_u32 s16, s9
	s_waitcnt lgkmcnt(3)
	v_mfma_f32_32x32x16_bf16 v[80:95], v[252:255], v[164:167], v[80:95]
	ds_read_b128 v[248:251], v205 offset:61440
	s_waitcnt lgkmcnt(3)
	v_mfma_f32_32x32x16_bf16 v[80:95], v[236:239], v[160:163], v[80:95]
	ds_read_b128 v[252:255], v207 offset:61440
	s_waitcnt lgkmcnt(3)
	v_mfma_f32_32x32x16_bf16 v[80:95], v[240:243], v[152:155], v[80:95]
	ds_read_b128 v[236:239], v209 offset:61440
	s_waitcnt lgkmcnt(3)
	v_mfma_f32_32x32x16_bf16 v[80:95], v[244:247], v[148:151], v[80:95]
	ds_read_b128 v[240:243], v211 offset:61440
	s_waitcnt lgkmcnt(3)
	v_mfma_f32_32x32x16_bf16 v[80:95], v[248:251], v[140:143], v[80:95]
	ds_read_b128 v[244:247], v225 offset:16384
	s_waitcnt lgkmcnt(3)
	v_mfma_f32_32x32x16_bf16 v[80:95], v[252:255], v[136:139], v[80:95]
	ds_read_b128 v[248:251], v225 offset:20480
	s_waitcnt lgkmcnt(3)
	v_mfma_f32_32x32x16_bf16 v[80:95], v[236:239], v[132:135], v[80:95]
	ds_read_b128 v[252:255], v225 offset:24576
	s_waitcnt lgkmcnt(3)
	v_mfma_f32_32x32x16_bf16 v[80:95], v[240:243], v[128:131], v[80:95]
	ds_read_b128 v[236:239], v225 offset:28672
	s_waitcnt lgkmcnt(3)
	v_mfma_f32_32x32x16_bf16 v[48:63], v[244:247], v[122:125], v[48:63]
	ds_read_b128 v[240:243], v226 offset:16384
	s_nop 8
	v_max_f32_e32 v113, v81, v81
	v_max_f32_e32 v126, v80, v80
	v_max_f32_e32 v113, v126, v113
	v_max3_f32 v113, v113, v82, v83
	v_max3_f32 v113, v113, v84, v85
	v_max3_f32 v113, v113, v86, v87
	v_max3_f32 v113, v113, v88, v89
	s_waitcnt lgkmcnt(3)
	v_mfma_f32_32x32x16_bf16 v[32:47], v[248:251], v[122:125], v[32:47]
	ds_read_b128 v[244:247], v226 offset:20480
	v_max3_f32 v113, v113, v90, v91
	v_max3_f32 v113, v113, v92, v93
	v_max3_f32 v113, v113, v94, v95
	s_waitcnt lgkmcnt(3)
	v_mfma_f32_32x32x16_bf16 v[16:31], v[252:255], v[122:125], v[16:31]
	ds_read_b128 v[248:251], v226 offset:24576
	s_waitcnt lgkmcnt(3)
	v_mfma_f32_32x32x16_bf16 v[0:15], v[236:239], v[122:125], v[0:15]
	ds_read_b128 v[252:255], v226 offset:28672
	v_cvt_pk_bf16_f32 v118, v104, v105
	v_cvt_pk_bf16_f32 v119, v106, v107
	v_cvt_pk_bf16_f32 v120, v108, v109
	v_cvt_pk_bf16_f32 v121, v110, v111
	s_nop 0
	s_waitcnt lgkmcnt(3)
	v_mfma_f32_32x32x16_bf16 v[48:63], v[240:243], v[118:121], v[48:63]
	ds_read_b128 v[236:239], v214 offset:32768
	s_waitcnt lgkmcnt(3)
	v_mfma_f32_32x32x16_bf16 v[32:47], v[244:247], v[118:121], v[32:47]
	ds_read_b128 v[240:243], v215 offset:32768
	s_waitcnt lgkmcnt(3)
	v_mfma_f32_32x32x16_bf16 v[16:31], v[248:251], v[118:121], v[16:31]
	ds_read_b128 v[244:247], v216 offset:32768
	ds_bpermute_b32 v114, v229, v113
	s_waitcnt lgkmcnt(4)
	v_mfma_f32_32x32x16_bf16 v[0:15], v[252:255], v[118:121], v[0:15]
	ds_read_b128 v[248:251], v217 offset:32768

.LBB0_869:
	v_exp_f32_e32 v96, v96
	v_exp_f32_e32 v97, v97
	v_exp_f32_e32 v98, v98
	v_mfma_f32_32x32x16_bf16 v[80:95], v[236:239], v[144:147], v[64:79]
	ds_read_b128 v[252:255], v218 offset:40960
	v_exp_f32_e32 v99, v99
	v_exp_f32_e32 v100, v100
	v_exp_f32_e32 v101, v101
	v_exp_f32_e32 v102, v102
	v_exp_f32_e32 v103, v103
	v_cvt_pk_bf16_f32 v122, v96, v97
	v_cvt_pk_bf16_f32 v123, v98, v99
	s_waitcnt lgkmcnt(3)
	v_mfma_f32_32x32x16_bf16 v[80:95], v[240:243], v[156:159], v[80:95]
	s_add_i32 s4, s8, 4
	s_cmp_ge_u32 s4, s9
	s_cbranch_scc1 .Lmla_dma_skip_t2
	s_add_u32 s98, s34, s60
	s_addc_u32 s99, s35, s59
	s_add_u32 s98, s98, 0x14108000
	s_addc_u32 s99, s99, 0
	s_add_u32 s100, s34, s62
	s_addc_u32 s101, s35, s61
	s_add_u32 s100, s100, 0x171b0200
	s_addc_u32 s101, s101, 0
	s_cmp_lg_u64 s[24:25], 0
	s_cselect_b32 s4, s100, s98
	s_cselect_b32 s5, s101, s99
	s_mov_b32 m0, s46
	v_mov_b32_e32 v234, s4
	v_mov_b32_e32 v235, s5
	v_lshl_add_u64 v[234:235], v[176:177], 1, v[234:235]
	global_load_lds_dwordx4 v[234:235], off
	s_cmp_lg_u64 s[26:27], 0
	s_cselect_b32 s4, s100, s98
	s_cselect_b32 s5, s101, s99
	s_mov_b32 m0, s47
	v_mov_b32_e32 v234, s4
	v_mov_b32_e32 v235, s5
	v_lshl_add_u64 v[234:235], v[178:179], 1, v[234:235]
	global_load_lds_dwordx4 v[234:235], off
	s_cmp_lg_u64 s[28:29], 0
	s_cselect_b32 s4, s100, s98
	s_cselect_b32 s5, s101, s99
	s_mov_b32 m0, s48
	v_mov_b32_e32 v234, s4
	v_mov_b32_e32 v235, s5
	v_lshl_add_u64 v[234:235], v[180:181], 1, v[234:235]
	global_load_lds_dwordx4 v[234:235], off
	s_cmp_lg_u64 s[30:31], 0
	s_cselect_b32 s4, s100, s98
	s_cselect_b32 s5, s101, s99
	s_mov_b32 m0, s49
	v_mov_b32_e32 v234, s4
	v_mov_b32_e32 v235, s5
	v_lshl_add_u64 v[234:235], v[182:183], 1, v[234:235]
	global_load_lds_dwordx4 v[234:235], off
	s_cmp_lg_u64 s[6:7], 0
	s_cselect_b32 s4, s100, s98
	s_cselect_b32 s5, s101, s99
	s_mov_b32 m0, s50
	v_mov_b32_e32 v234, s4
	v_mov_b32_e32 v235, s5
	v_lshl_add_u64 v[234:235], v[184:185], 1, v[234:235]
	global_load_lds_dwordx4 v[234:235], off
.Lmla_dma_skip_t2:
	ds_read_b128 v[236:239], v219 offset:40960
	v_cvt_pk_bf16_f32 v124, v100, v101
	v_cvt_pk_bf16_f32 v125, v102, v103
	v_exp_f32_e32 v104, v104
	v_exp_f32_e32 v105, v105
	v_exp_f32_e32 v106, v106
	v_exp_f32_e32 v107, v107
	s_waitcnt lgkmcnt(3)
	v_mfma_f32_32x32x16_bf16 v[80:95], v[244:247], v[168:171], v[80:95]
	ds_read_b128 v[240:243], v220 offset:40960
	v_exp_f32_e32 v108, v108
	v_exp_f32_e32 v109, v109
	v_exp_f32_e32 v110, v110
	v_exp_f32_e32 v111, v111
	s_add_i32 s4, s8, 4
	s_cmp_ge_u32 s4, s9
	s_waitcnt lgkmcnt(3)
	v_mfma_f32_32x32x16_bf16 v[80:95], v[248:251], v[172:175], v[80:95]
	ds_read_b128 v[244:247], v221 offset:40960
	s_waitcnt lgkmcnt(3)
	v_mfma_f32_32x32x16_bf16 v[80:95], v[252:255], v[164:167], v[80:95]
	ds_read_b128 v[248:251], v206 offset:20480
	s_waitcnt lgkmcnt(3)
	v_mfma_f32_32x32x16_bf16 v[80:95], v[236:239], v[160:163], v[80:95]
	ds_read_b128 v[252:255], v208 offset:20480
	s_waitcnt lgkmcnt(3)
	v_mfma_f32_32x32x16_bf16 v[80:95], v[240:243], v[152:155], v[80:95]
	ds_read_b128 v[236:239], v210 offset:20480
	s_waitcnt lgkmcnt(3)
	v_mfma_f32_32x32x16_bf16 v[80:95], v[244:247], v[148:151], v[80:95]
	ds_read_b128 v[240:243], v212 offset:20480
	s_waitcnt lgkmcnt(3)
	v_mfma_f32_32x32x16_bf16 v[80:95], v[248:251], v[140:143], v[80:95]
	ds_read_b128 v[244:247], v225 offset:32768
	s_waitcnt lgkmcnt(3)
	v_mfma_f32_32x32x16_bf16 v[80:95], v[252:255], v[136:139], v[80:95]
	ds_read_b128 v[248:251], v225 offset:36864
	s_waitcnt lgkmcnt(3)
	v_mfma_f32_32x32x16_bf16 v[80:95], v[236:239], v[132:135], v[80:95]
	ds_read_b128 v[252:255], v225 offset:40960
	s_waitcnt lgkmcnt(3)
	v_mfma_f32_32x32x16_bf16 v[80:95], v[240:243], v[128:131], v[80:95]
	ds_read_b128 v[236:239], v225 offset:45056
	s_waitcnt lgkmcnt(3)
	v_mfma_f32_32x32x16_bf16 v[48:63], v[244:247], v[122:125], v[48:63]
	ds_read_b128 v[240:243], v226 offset:32768
	s_nop 8
	v_max_f32_e32 v113, v81, v81
	v_max_f32_e32 v126, v80, v80
	v_max_f32_e32 v113, v126, v113
	v_max3_f32 v113, v113, v82, v83
	v_max3_f32 v113, v113, v84, v85
	v_max3_f32 v113, v113, v86, v87
	v_max3_f32 v113, v113, v88, v89
	s_waitcnt lgkmcnt(3)
	v_mfma_f32_32x32x16_bf16 v[32:47], v[248:251], v[122:125], v[32:47]
	ds_read_b128 v[244:247], v226 offset:36864
	v_max3_f32 v113, v113, v90, v91
	v_max3_f32 v113, v113, v92, v93
	v_max3_f32 v113, v113, v94, v95
	s_waitcnt lgkmcnt(3)
	v_mfma_f32_32x32x16_bf16 v[16:31], v[252:255], v[122:125], v[16:31]
	ds_read_b128 v[248:251], v226 offset:40960
	s_waitcnt lgkmcnt(3)
	v_mfma_f32_32x32x16_bf16 v[0:15], v[236:239], v[122:125], v[0:15]
	ds_read_b128 v[252:255], v226 offset:45056
	v_cvt_pk_bf16_f32 v118, v104, v105
	v_cvt_pk_bf16_f32 v119, v106, v107
	v_cvt_pk_bf16_f32 v120, v108, v109
	v_cvt_pk_bf16_f32 v121, v110, v111
	s_nop 0
	s_waitcnt lgkmcnt(3)
	v_mfma_f32_32x32x16_bf16 v[48:63], v[240:243], v[118:121], v[48:63]
	ds_read_b128 v[236:239], v214
	s_waitcnt lgkmcnt(3)
	v_mfma_f32_32x32x16_bf16 v[32:47], v[244:247], v[118:121], v[32:47]
	ds_read_b128 v[240:243], v215
	s_waitcnt lgkmcnt(3)
	v_mfma_f32_32x32x16_bf16 v[16:31], v[248:251], v[118:121], v[16:31]
	ds_read_b128 v[244:247], v216
	ds_bpermute_b32 v114, v229, v113
	s_waitcnt lgkmcnt(4)
	v_mfma_f32_32x32x16_bf16 v[0:15], v[252:255], v[118:121], v[0:15]
	ds_read_b128 v[248:251], v217

	.amdhsa_kernel _Z14fwd_megakernel4Args
		.amdhsa_group_segment_fixed_size 0
		.amdhsa_private_segment_fixed_size 0
		.amdhsa_kernarg_size 520
		.amdhsa_user_sgpr_count 2
		.amdhsa_user_sgpr_dispatch_ptr 0
		.amdhsa_user_sgpr_queue_ptr 0
		.amdhsa_user_sgpr_kernarg_segment_ptr 1
		.amdhsa_user_sgpr_dispatch_id 0
		.amdhsa_user_sgpr_kernarg_preload_length 0
		.amdhsa_user_sgpr_kernarg_preload_offset 0
		.amdhsa_user_sgpr_private_segment_size 0
		.amdhsa_uses_dynamic_stack 0
		.amdhsa_enable_private_segment 0
		.amdhsa_system_sgpr_workgroup_id_x 1
		.amdhsa_system_sgpr_workgroup_id_y 0
		.amdhsa_system_sgpr_workgroup_id_z 0
		.amdhsa_system_sgpr_workgroup_info 0
		.amdhsa_system_vgpr_workitem_id 2
		.amdhsa_next_free_vgpr 256
		.amdhsa_next_free_sgpr 102
		.amdhsa_accum_offset 256
		.amdhsa_reserve_vcc 1
		.amdhsa_float_round_mode_32 0
		.amdhsa_float_round_mode_16_64 0
		.amdhsa_float_denorm_mode_32 3
		.amdhsa_float_denorm_mode_16_64 3
		.amdhsa_dx10_clamp 1
		.amdhsa_ieee_mode 1
		.amdhsa_fp16_overflow 0
		.amdhsa_tg_split 0
		.amdhsa_exception_fp_ieee_invalid_op 0
		.amdhsa_exception_fp_denorm_src 0
		.amdhsa_exception_fp_ieee_div_zero 0
		.amdhsa_exception_fp_ieee_overflow 0
		.amdhsa_exception_fp_ieee_underflow 0
		.amdhsa_exception_fp_ieee_inexact 0
		.amdhsa_exception_int_div_zero 0
	.end_amdhsa_kernel

amdhsa.kernels:
  - .agpr_count:     0
    .args:
      - .offset:         0
        .size:           264
        .value_kind:     by_value
      - .offset:         264
        .size:           4
        .value_kind:     hidden_block_count_x
      - .offset:         268
        .size:           4
        .value_kind:     hidden_block_count_y
      - .offset:         272
        .size:           4
        .value_kind:     hidden_block_count_z
      - .offset:         276
        .size:           2
        .value_kind:     hidden_group_size_x
      - .offset:         278
        .size:           2
        .value_kind:     hidden_group_size_y
      - .offset:         280
        .size:           2
        .value_kind:     hidden_group_size_z
      - .offset:         282
        .size:           2
        .value_kind:     hidden_remainder_x
      - .offset:         284
        .size:           2
        .value_kind:     hidden_remainder_y
      - .offset:         286
        .size:           2
        .value_kind:     hidden_remainder_z
      - .offset:         304
        .size:           8
        .value_kind:     hidden_global_offset_x
      - .offset:         312
        .size:           8
        .value_kind:     hidden_global_offset_y
      - .offset:         320
        .size:           8
        .value_kind:     hidden_global_offset_z
      - .offset:         328
        .size:           2
        .value_kind:     hidden_grid_dims
      - .offset:         352
        .size:           8
        .value_kind:     hidden_multigrid_sync_arg
      - .offset:         384
        .size:           4
        .value_kind:     hidden_dynamic_lds_size
    .group_segment_fixed_size: 0
    .kernarg_segment_align: 8
    .kernarg_segment_size: 520
    .language:       OpenCL C
    .language_version:
      - 2
      - 0
    .max_flat_workgroup_size: 512
    .name:           _Z14fwd_megakernel4Args
    .private_segment_fixed_size: 0
    .sgpr_count:     108
    .sgpr_spill_count: 2
    .symbol:         _Z14fwd_megakernel4Args.kd
    .uniform_work_group_size: 1
    .uses_dynamic_stack: false
    .vgpr_count:     256
    .vgpr_spill_count: 0
    .wavefront_size: 64
